# v67 + scan waves at s_setprio 3
# speedup vs baseline: 1.0119x; 1.0014x over previous
.LBB0_399:
	s_setprio 0
	v_mov_b32_e32 v1, v198
	s_waitcnt lgkmcnt(0)
	s_barrier
	s_nop 0
	v_cmp_eq_u32_e32 vcc, 0, v1
	s_and_saveexec_b64 s[0:1], vcc
	s_cbranch_execz .LBB0_401
	s_cmp_lg_u32 s32, 0
	s_cbranch_scc1 .Lscan_direct
	v_mov_b64_e32 v[4:5], s[14:15]
	flat_atomic_add v1, v[4:5], v199 sc0
	v_mov_b32_e32 v2, s2
	s_waitcnt vmcnt(0) lgkmcnt(0)
	v_add_u32_e32 v1, 64, v1
	s_branch .Lscan_wr

.LBB0_487:
	s_and_b64 vcc, exec, s[0:1]
	s_cbranch_vccz .LBB0_397
	s_setprio 3
	v_mov_b32_e32 v76, v198
	v_mov_b64_e32 v[4:5], s[16:17]
	flat_load_dwordx2 v[100:101], v[4:5]
	s_lshl_b32 s4, s75, 6
	s_and_b32 s0, s75, 1
	s_ashr_i32 s1, s75, 3
	s_and_b32 s4, s4, 0xffffff80
	v_add_u32_e32 v78, 0x100, v76
	v_add_u32_e32 v84, 0x200, v76
	v_add_u32_e32 v86, 0x300, v76
	v_add_u32_e32 v88, 0x400, v76
	v_add_u32_e32 v90, 0x500, v76
	v_add_u32_e32 v92, 0x600, v76
	v_add_u32_e32 v94, 0x700, v76
	s_mul_hi_i32 s7, s1, 0x3800000
	s_mul_i32 s8, s1, 0x3800000
	s_lshl_b32 s9, s0, 6
	s_lshl_b32 s18, s0, 13
	v_ashrrev_i32_e32 v77, 31, v76
	v_ashrrev_i32_e32 v79, 31, v78
	v_ashrrev_i32_e32 v85, 31, v84
	v_ashrrev_i32_e32 v87, 31, v86
	v_ashrrev_i32_e32 v89, 31, v88
	v_ashrrev_i32_e32 v91, 31, v90
	v_ashrrev_i32_e32 v93, 31, v92
	v_ashrrev_i32_e32 v95, 31, v94
	v_lshlrev_b64 v[96:97], 4, v[76:77]
	v_lshlrev_b64 v[98:99], 4, v[78:79]
	v_lshlrev_b64 v[110:111], 4, v[84:85]
	v_lshlrev_b64 v[108:109], 4, v[86:87]
	v_lshlrev_b64 v[106:107], 4, v[88:89]
	v_lshlrev_b64 v[104:105], 4, v[90:91]
	v_lshlrev_b64 v[122:123], 4, v[92:93]
	v_lshlrev_b64 v[120:121], 4, v[94:95]
	s_lshl_b32 s5, s75, 7
	s_and_b32 s10, s5, 0x300
	s_ashr_i32 s5, s4, 31
	v_and_b32_e32 v79, 63, v76
	v_bfe_u32 v87, v76, 4, 2
	v_ashrrev_i32_e32 v77, 6, v76
	s_mul_i32 s52, s4, 0x12000
	v_lshlrev_b32_e32 v78, 4, v78
	v_lshlrev_b32_e32 v89, 4, v90
	v_lshlrev_b32_e32 v90, 4, v92
	v_lshl_add_u32 v2, v79, 4, 0
	v_lshlrev_b32_e32 v92, 3, v79
	v_mul_hi_u32_u24_e32 v79, 0x7000, v87
	v_mul_u32_u24_e32 v87, 0x7000, v87
	v_and_b32_e32 v85, 15, v76
	s_mul_hi_i32 s11, s4, 0x12000
	v_lshlrev_b32_e32 v1, 4, v76
	v_lshl_add_u32 v76, v77, 4, s9
	v_add_u32_e32 v124, 0, v78
	v_or_b32_e32 v79, s7, v79
	v_or_b32_e32 v78, s8, v87
	v_mad_i64_i32 v[102:103], s[8:9], s4, v210, v[96:97]
	v_lshl_add_u32 v93, v77, 11, 0
	v_ashrrev_i32_e32 v77, 31, v76
	v_or_b32_e32 v78, s10, v78
	v_mov_b32_e32 v4, 0
	v_lshlrev_b32_e32 v84, 4, v84
	v_lshlrev_b32_e32 v86, 4, v86
	v_lshlrev_b32_e32 v88, 4, v88
	v_lshlrev_b32_e32 v91, 4, v94
	v_lshl_add_u64 v[114:115], v[76:77], 1, v[78:79]
	s_movk_i32 s6, 0x7f
	v_mov_b32_e32 v5, v4
	v_mov_b32_e32 v6, v4
	v_mov_b32_e32 v7, v4
	v_mov_b32_e32 v16, v4
	v_mov_b32_e32 v17, v4
	v_mov_b32_e32 v18, v4
	v_mov_b32_e32 v19, v4
	v_add_u32_e32 v1, 0, v1
	v_add_u32_e32 v125, 0, v84
	v_add_u32_e32 v126, 0, v86
	v_add_u32_e32 v127, 0, v88
	v_add_u32_e32 v128, 0, v89
	v_add_u32_e32 v129, 0, v90
	v_add_u32_e32 v130, 0, v91
	v_add_u32_e32 v131, v93, v92
	s_waitcnt vmcnt(0) lgkmcnt(0)
	v_readfirstlane_b32 s86, v100
	v_readfirstlane_b32 s87, v101
	v_mad_i64_i32 v[8:9], s[0:1], s4, v210, v[100:101]
	v_lshl_add_u64 v[10:11], v[8:9], 0, s[34:35]
	v_lshl_add_u64 v[8:9], v[8:9], 0, s[44:45]
	v_lshl_add_u64 v[12:13], v[10:11], 0, v[96:97]
	v_lshl_add_u64 v[14:15], v[10:11], 0, v[98:99]
	v_lshl_add_u64 v[20:21], v[10:11], 0, v[110:111]
	v_lshl_add_u64 v[24:25], v[10:11], 0, v[108:109]
	v_lshl_add_u64 v[28:29], v[10:11], 0, v[106:107]
	v_lshl_add_u64 v[32:33], v[10:11], 0, v[104:105]
	v_lshl_add_u64 v[36:37], v[10:11], 0, v[122:123]
	v_lshl_add_u64 v[40:41], v[10:11], 0, v[120:121]
	v_lshl_add_u64 v[30:31], v[8:9], 0, v[96:97]
	v_lshl_add_u64 v[34:35], v[8:9], 0, v[98:99]
	v_lshl_add_u64 v[38:39], v[8:9], 0, v[110:111]
	v_lshl_add_u64 v[42:43], v[8:9], 0, v[108:109]
	v_lshl_add_u64 v[44:45], v[8:9], 0, v[106:107]
	v_lshl_add_u64 v[72:73], v[10:11], 0, s[18:19]
	v_lshl_add_u64 v[46:47], v[8:9], 0, v[104:105]
	global_load_dwordx4 v[8:11], v[12:13], off
	s_nop 0
	global_load_dwordx4 v[12:15], v[14:15], off
	s_nop 0
	global_load_dwordx4 v[20:23], v[20:21], off
	s_nop 0
	global_load_dwordx4 v[24:27], v[24:25], off
	s_nop 0
	global_load_dwordx4 v[48:51], v[30:31], off
	global_load_dwordx4 v[52:55], v[34:35], off
	s_nop 0
	global_load_dwordx4 v[28:31], v[28:29], off
	s_nop 0
	global_load_dwordx4 v[32:35], v[32:33], off
	s_nop 0
	global_load_dwordx4 v[56:59], v[38:39], off
	global_load_dwordx4 v[60:63], v[42:43], off
	s_nop 0
	global_load_dwordx4 v[36:39], v[36:37], off
	s_nop 0
	global_load_dwordx4 v[40:43], v[40:41], off
	s_nop 0
	global_load_dwordx4 v[64:67], v[44:45], off
	global_load_dwordx4 v[68:71], v[46:47], off
	v_lshl_add_u64 v[44:45], v[72:73], 0, s[46:47]
	v_lshl_add_u64 v[46:47], v[44:45], 0, v[96:97]
	v_lshl_add_u64 v[44:45], v[44:45], 0, v[98:99]
	global_load_dwordx4 v[72:75], v[46:47], off
	global_load_dwordx4 v[80:83], v[44:45], off
	s_lshl_b64 s[0:1], s[4:5], 2
	s_add_u32 s0, s0, 0x2ce00000
	s_addc_u32 s1, s1, 0
	s_or_b32 s7, s52, s18
	v_mad_i64_i32 v[104:105], s[8:9], s4, v210, v[104:105]
	v_mad_i64_i32 v[106:107], s[8:9], s4, v210, v[106:107]
	v_mad_i64_i32 v[108:109], s[8:9], s4, v210, v[108:109]
	v_mad_i64_i32 v[110:111], s[8:9], s4, v210, v[110:111]
	v_mad_i64_i32 v[112:113], s[4:5], s4, v210, v[98:99]
	s_add_u32 s4, s7, 0x2e020000
	s_addc_u32 s5, s11, 0
	v_lshl_add_u64 v[116:117], s[4:5], 0, v[98:99]
	v_lshl_add_u64 v[118:119], s[4:5], 0, v[96:97]
	s_add_u32 s4, s52, 0x2e012000
	s_addc_u32 s5, s11, 0
	v_mov_b32_e32 v44, v4
	v_mov_b32_e32 v45, v4
	v_mov_b32_e32 v46, v4
	v_mov_b32_e32 v47, v4
	v_lshl_or_b32 v114, v85, 1, v114
	v_lshl_add_u64 v[120:121], s[4:5], 0, v[120:121]
	v_lshl_add_u64 v[122:123], s[4:5], 0, v[122:123]
	v_mov_b32_e32 v76, v4
	v_mov_b32_e32 v77, v4
	v_mov_b32_e32 v78, v4
	v_mov_b32_e32 v79, v4
	v_mov_b32_e32 v84, v4
	v_mov_b32_e32 v85, v4
	v_mov_b32_e32 v86, v4
	v_mov_b32_e32 v87, v4
	v_mov_b32_e32 v88, v4
	v_mov_b32_e32 v89, v4
	v_mov_b32_e32 v90, v4
	v_mov_b32_e32 v91, v4
	v_mov_b32_e32 v92, v4
	v_mov_b32_e32 v93, v4
	v_mov_b32_e32 v94, v4
	v_mov_b32_e32 v95, v4
	v_mov_b32_e32 v96, v4
	v_mov_b32_e32 v97, v4
	v_mov_b32_e32 v98, v4
	v_mov_b32_e32 v99, v4
	s_waitcnt vmcnt(15)
	ds_write_b128 v1, v[8:11]
	s_waitcnt vmcnt(11)
	ds_write_b128 v1, v[48:51] offset:32768
	ds_write_b128 v124, v[12:15]
	s_waitcnt vmcnt(10)
	ds_write_b128 v124, v[52:55] offset:32768
	ds_write_b128 v125, v[20:23]
	s_waitcnt vmcnt(7)
	ds_write_b128 v125, v[56:59] offset:32768
	ds_write_b128 v126, v[24:27]
	s_waitcnt vmcnt(6)
	ds_write_b128 v126, v[60:63] offset:32768
	ds_write_b128 v127, v[28:31]
	s_waitcnt vmcnt(3)
	ds_write_b128 v127, v[64:67] offset:32768
	ds_write_b128 v128, v[32:35]
	s_waitcnt vmcnt(2)
	ds_write_b128 v128, v[68:71] offset:32768
	ds_write_b128 v129, v[36:39]
	ds_write_b128 v130, v[40:43]
	s_waitcnt vmcnt(1)
	ds_write_b128 v129, v[72:75] offset:32768
	s_waitcnt vmcnt(0)
	ds_write_b128 v130, v[80:83] offset:32768
	s_waitcnt lgkmcnt(0)
	s_barrier
	s_branch .LBB0_490
